# replace cg grid sync after P0 with sharded device-scope counter barrier
# speedup vs baseline: 1.0129x; 1.0129x over previous
; #define LAS __attribute__((address_space(3)))
; __device__ __forceinline__ unsigned xb_xcc_id() { return (unsigned)__builtin_amdgcn_s_getreg((3 << 11) | 20) & 0xFu; }
; __global__ void __launch_bounds__(512, 2) hymba_fwd(Params p) {
;     extern __shared__ __attribute__((aligned(16))) unsigned char shm[];
;     LAS unsigned char* lds = (LAS unsigned char*)shm;
;     cg::grid_group grid = cg::this_grid();
;     unsigned char* ws = p.ws;
;     const int G = gridDim.x, c = blockIdx.x;
;     XB xb; xb.bar = (unsigned*)(ws + OFF_BAR); xb.x = xb_xcc_id();
;     if (c == 0) for (int i = threadIdx.x; i < 2176; i += 512) xb.bar[1024 + i] = 0u;
;     if (threadIdx.x == 0) xb.bar[3200 + c] = xb.x;
_Z9hymba_fwd6Params:
	s_load_dwordx2 s[82:83], s[0:1], 0x100
	s_load_dword s33, s[0:1], 0x108
	s_add_u32 s24, s0, 0x108
	s_addc_u32 s25, s1, 0
	s_getreg_b32 s3, hwreg(HW_REG_XCC_ID, 0, 4)
	s_waitcnt lgkmcnt(0)
	s_add_u32 s4, s82, 0x1b6e900
	s_addc_u32 s5, s83, 0
	s_cmp_eq_u32 s2, 0
	v_writelane_b32 v253, s4, 0
	s_mov_b32 s8, 0
	s_cselect_b64 s[6:7], -1, 0
	s_cmp_lg_u32 s2, 0
	v_and_b32_e32 v132, 0x3ff, v0
	v_writelane_b32 v253, s5, 1
	s_cbranch_scc1 .LBB0_8
	v_cmp_eq_u32_e32 vcc, 0, v132
	s_and_saveexec_b64 s[98:99], vcc
	s_cbranch_execz .Lgs_init_done
	s_load_dwordx2 s[100:101], s[24:25], 0x58
	v_mov_b32_e32 v1, 0
	v_mov_b32_e32 v2, 0x3600
	global_store_dword v2, v1, s[4:5] offset:0 sc0 sc1
	global_store_dword v2, v1, s[4:5] offset:128 sc0 sc1
	global_store_dword v2, v1, s[4:5] offset:256 sc0 sc1
	global_store_dword v2, v1, s[4:5] offset:384 sc0 sc1
	global_store_dword v2, v1, s[4:5] offset:512 sc0 sc1
	global_store_dword v2, v1, s[4:5] offset:640 sc0 sc1
	global_store_dword v2, v1, s[4:5] offset:768 sc0 sc1
	global_store_dword v2, v1, s[4:5] offset:896 sc0 sc1
	global_store_dword v2, v1, s[4:5] offset:1024 sc0 sc1
	global_store_dword v2, v1, s[4:5] offset:1152 sc0 sc1
	global_store_dword v2, v1, s[4:5] offset:1280 sc0 sc1
	global_store_dword v2, v1, s[4:5] offset:1408 sc0 sc1
	global_store_dword v2, v1, s[4:5] offset:1536 sc0 sc1
	global_store_dword v2, v1, s[4:5] offset:1664 sc0 sc1
	global_store_dword v2, v1, s[4:5] offset:1792 sc0 sc1
	global_store_dword v2, v1, s[4:5] offset:1920 sc0 sc1
	global_store_dword v2, v1, s[4:5] offset:2048 sc0 sc1
	s_waitcnt vmcnt(0) lgkmcnt(0)
	v_mov_b32_e32 v2, 1
	global_atomic_add v1, v2, s[100:101] offset:32
.Lgs_init_done:
	s_or_b64 exec, exec, s[98:99]
	v_sub_u32_e32 v1, 0x87f, v132
	v_lshrrev_b32_e32 v2, 9, v1
	v_add_u32_e32 v1, 2, v2
	v_add_u32_e32 v133, 0x200, v132
	v_and_b32_e32 v3, 14, v1
	v_mov_b32_e32 v1, v2
	s_mov_b64 s[10:11], 0
	s_mov_b32 s9, 1
	v_mov_b32_e32 v5, 0
	s_mov_b32 s12, s8
	v_mov_b64_e32 v[6:7], v[132:133]
	s_branch .LBB0_3

; __device__ __forceinline__ unsigned xb_ld(unsigned* p) { return __hip_atomic_load(p, __ATOMIC_RELAXED, __HIP_MEMORY_SCOPE_AGENT); }
; __device__ __forceinline__ unsigned xb_add(unsigned* p, unsigned v) { return __hip_atomic_fetch_add(p, v, __ATOMIC_RELAXED, __HIP_MEMORY_SCOPE_AGENT); }
; __device__ __forceinline__ void xcd_barrier(const XB& b) {
;     __syncthreads();
;     if (threadIdx.x == 0) {
;         unsigned* bar = b.bar;
;         __builtin_amdgcn_fence(__ATOMIC_RELEASE, "agent");
;         asm volatile("s_waitcnt vmcnt(0)" ::: "memory");
;         const unsigned old = xb_add(&bar[XB_XSUB(b.x)], 1u);
;         const unsigned gen = old / b.nloc;
;         if (old + 1u == (gen + 1u) * b.nloc) {
;             const unsigned og = xb_add(&bar[XB_TOP], 1u);
;             const unsigned target = (og / b.nx + 1u) * b.nx;
;             if (og + 1u != target) while (xb_ld(&bar[XB_TOP]) < target) __builtin_amdgcn_s_sleep(1);
;             xb_add(&bar[XB_XGEN(b.x)], 1u);
;         } else {
;             while (xb_ld(&bar[XB_XGEN(b.x)]) == gen) __builtin_amdgcn_s_sleep(1);
;         }
;         __builtin_amdgcn_fence(__ATOMIC_ACQUIRE, "agent");
;         asm volatile("s_waitcnt vmcnt(0)" ::: "memory");
;     }
;     __syncthreads();
; }
; __global__ void __launch_bounds__(512, 2) hymba_fwd(Params p) {
;     ...
;     p0_prep(p, lds);
;     grid.sync();
.LBB0_62:
	s_or_b64 exec, exec, s[10:11]
	v_lshrrev_b32_e32 v1, 20, v0
	v_lshrrev_b32_e32 v0, 10, v0
	v_or_b32_e32 v0, v0, v1
	s_movk_i32 s0, 0x3ff
	v_and_or_b32 v0, v0, s0, v132
	v_cmp_eq_u32_e32 vcc, 0, v0
	s_waitcnt lgkmcnt(0)
	s_barrier
	s_and_saveexec_b64 s[0:1], vcc
	s_cbranch_execz .LBB0_72
	s_load_dwordx2 s[6:7], s[24:25], 0x58
	v_mov_b32_e32 v2, 0
	v_readlane_b32 s8, v253, 0
	v_readlane_b32 s9, v253, 1
	s_and_b32 s10, s2, 7
	s_lshl_b32 s11, s10, 7
	s_addk_i32 s11, 0x3600
	v_mov_b32_e32 v4, s11
	s_waitcnt lgkmcnt(0)
	global_load_dword v0, v2, s[6:7] offset:32 sc1
	buffer_wbl2 sc1
	s_waitcnt vmcnt(0)
.Lgs_flagpoll:
	v_readfirstlane_b32 s11, v0
	s_and_b32 s11, s11, 0xffff
	s_cmp_lg_u32 s11, 0
	s_cbranch_scc1 .Lgs_arrive
	s_sleep 1
	global_load_dword v0, v2, s[6:7] offset:32 sc1
	s_waitcnt vmcnt(0)
	s_branch .Lgs_flagpoll
.Lgs_arrive:
	v_mov_b32_e32 v1, 1
	global_atomic_add v0, v4, v1, s[8:9] sc0
	s_add_i32 s3, s33, 7
	s_sub_i32 s3, s3, s10
	s_lshr_b32 s3, s3, 3
	s_add_i32 s3, s3, -1
	v_add_u32_e32 v5, 0x480, v4
	s_waitcnt vmcnt(0)
	v_readfirstlane_b32 s11, v0
	s_cmp_lg_u32 s11, s3
	s_cbranch_scc1 .Lgs_gen
	v_mov_b32_e32 v4, 0x3a00
	global_atomic_add v4, v1, s[8:9]
	s_min_u32 s3, s33, 8
.Lgs_top:
	s_sleep 1
	global_load_dword v0, v4, s[8:9] sc1
	s_waitcnt vmcnt(0)
	v_readfirstlane_b32 s11, v0
	s_cmp_lt_u32 s11, s3
	s_cbranch_scc1 .Lgs_top
	global_atomic_add v5, v1, s[8:9]
	s_branch .Lgs_done
.Lgs_gen:
	s_sleep 1
	global_load_dword v0, v5, s[8:9] sc1
	s_waitcnt vmcnt(0)
	v_readfirstlane_b32 s11, v0
	s_cmp_eq_u32 s11, 0
	s_cbranch_scc1 .Lgs_gen
.Lgs_done:
	s_cmp_lg_u32 s2, 0
	s_cbranch_scc1 .Lgs_inv
	v_mov_b32_e32 v1, -1
	global_atomic_add v2, v1, s[6:7] offset:32
.Lgs_inv:
	s_waitcnt vmcnt(0)
	buffer_inv sc1

; __global__ void __launch_bounds__(512, 2) hymba_fwd(Params p) {
	.amdhsa_kernel _Z9hymba_fwd6Params
		.amdhsa_group_segment_fixed_size 0
		.amdhsa_private_segment_fixed_size 0
		.amdhsa_kernarg_size 520
		.amdhsa_user_sgpr_count 2
		.amdhsa_user_sgpr_dispatch_ptr 0
		.amdhsa_user_sgpr_queue_ptr 0
		.amdhsa_user_sgpr_kernarg_segment_ptr 1
		.amdhsa_user_sgpr_dispatch_id 0
		.amdhsa_user_sgpr_kernarg_preload_length 0
		.amdhsa_user_sgpr_kernarg_preload_offset 0
		.amdhsa_user_sgpr_private_segment_size 0
		.amdhsa_uses_dynamic_stack 0
		.amdhsa_enable_private_segment 0
		.amdhsa_system_sgpr_workgroup_id_x 1
		.amdhsa_system_sgpr_workgroup_id_y 0
		.amdhsa_system_sgpr_workgroup_id_z 0
		.amdhsa_system_sgpr_workgroup_info 0
		.amdhsa_system_vgpr_workitem_id 2
		.amdhsa_next_free_vgpr 254
		.amdhsa_next_free_sgpr 102
		.amdhsa_accum_offset 256
		.amdhsa_reserve_vcc 1
		.amdhsa_float_round_mode_32 0
		.amdhsa_float_round_mode_16_64 0
		.amdhsa_float_denorm_mode_32 3
		.amdhsa_float_denorm_mode_16_64 3
		.amdhsa_dx10_clamp 1
		.amdhsa_ieee_mode 1
		.amdhsa_fp16_overflow 0
		.amdhsa_tg_split 0
		.amdhsa_exception_fp_ieee_invalid_op 0
		.amdhsa_exception_fp_denorm_src 0
		.amdhsa_exception_fp_ieee_div_zero 0
		.amdhsa_exception_fp_ieee_overflow 0
		.amdhsa_exception_fp_ieee_underflow 0
		.amdhsa_exception_fp_ieee_inexact 0
		.amdhsa_exception_int_div_zero 0
	.end_amdhsa_kernel

; __global__ void __launch_bounds__(512, 2) hymba_fwd(Params p) {
amdhsa.kernels:
  - .agpr_count:     0
    .args:
      - .offset:         0
        .size:           264
        .value_kind:     by_value
      - .offset:         264
        .size:           4
        .value_kind:     hidden_block_count_x
      - .offset:         268
        .size:           4
        .value_kind:     hidden_block_count_y
      - .offset:         272
        .size:           4
        .value_kind:     hidden_block_count_z
      - .offset:         276
        .size:           2
        .value_kind:     hidden_group_size_x
      - .offset:         278
        .size:           2
        .value_kind:     hidden_group_size_y
      - .offset:         280
        .size:           2
        .value_kind:     hidden_group_size_z
      - .offset:         282
        .size:           2
        .value_kind:     hidden_remainder_x
      - .offset:         284
        .size:           2
        .value_kind:     hidden_remainder_y
      - .offset:         286
        .size:           2
        .value_kind:     hidden_remainder_z
      - .offset:         304
        .size:           8
        .value_kind:     hidden_global_offset_x
      - .offset:         312
        .size:           8
        .value_kind:     hidden_global_offset_y
      - .offset:         320
        .size:           8
        .value_kind:     hidden_global_offset_z
      - .offset:         328
        .size:           2
        .value_kind:     hidden_grid_dims
      - .offset:         352
        .size:           8
        .value_kind:     hidden_multigrid_sync_arg
      - .offset:         384
        .size:           4
        .value_kind:     hidden_dynamic_lds_size
    .group_segment_fixed_size: 0
    .kernarg_segment_align: 8
    .kernarg_segment_size: 520
    .language:       OpenCL C
    .language_version:
      - 2
      - 0
    .max_flat_workgroup_size: 512
    .name:           _Z9hymba_fwd6Params
    .private_segment_fixed_size: 0
    .sgpr_count:     108
    .sgpr_spill_count: 36
    .symbol:         _Z9hymba_fwd6Params.kd
    .uniform_work_group_size: 1
    .uses_dynamic_stack: false
    .vgpr_count:     254
    .vgpr_spill_count: 0
    .wavefront_size: 64
